# batched context-key conversion guarded by grid size (original path kept for any other grid)
# speedup vs baseline: 1.0101x; 1.0101x over previous
.LBB0_668:
	s_andn2_saveexec_b64 s[6:7], s[6:7]
	s_cbranch_execz .LBB0_665
	s_cmpk_lg_u32 s9, 0x200
	s_cbranch_scc1 .Lxb_orig_668
	v_cmp_le_i32_e32 vcc, s9, v20
	s_cbranch_vccnz .LBB0_665
	v_and_or_b32 v128, v27, s16, v23
	v_ashrrev_i32_e32 v129, 19, v27
	v_lshrrev_b32_e32 v128, 10, v128
	v_lshl_or_b32 v126, v129, 10, v128
	v_ashrrev_i32_e32 v127, 31, v126
	v_lshlrev_b64 v[126:127], 12, v[126:127]
	v_lshl_add_u64 v[126:127], v[4:5], 0, v[126:127]
	global_load_dwordx4 v[118:121], v[126:127], off
	global_load_dwordx4 v[122:125], v[126:127], off offset:16
	v_mad_i32_i24 v129, v129, s8, v41
	v_or_b32_e32 v126, v129, v128
	v_ashrrev_i32_e32 v127, 31, v129
	v_lshlrev_b64 v[126:127], 11, v[126:127]
	v_lshl_add_u64 v[126:127], v[2:3], 0, v[126:127]
	s_mul_i32 s98, s13, 1
	v_add_u32_e32 v141, s98, v27
	v_and_or_b32 v140, v141, s16, v23
	v_ashrrev_i32_e32 v141, 19, v141
	v_lshrrev_b32_e32 v140, 10, v140
	v_lshl_or_b32 v138, v141, 10, v140
	v_ashrrev_i32_e32 v139, 31, v138
	v_lshlrev_b64 v[138:139], 12, v[138:139]
	v_lshl_add_u64 v[138:139], v[4:5], 0, v[138:139]
	global_load_dwordx4 v[130:133], v[138:139], off
	global_load_dwordx4 v[134:137], v[138:139], off offset:16
	v_mad_i32_i24 v141, v141, s8, v41
	v_or_b32_e32 v138, v141, v140
	v_ashrrev_i32_e32 v139, 31, v141
	v_lshlrev_b64 v[138:139], 11, v[138:139]
	v_lshl_add_u64 v[138:139], v[2:3], 0, v[138:139]
	s_mul_i32 s98, s13, 2
	v_add_u32_e32 v153, s98, v27
	v_and_or_b32 v152, v153, s16, v23
	v_ashrrev_i32_e32 v153, 19, v153
	v_lshrrev_b32_e32 v152, 10, v152
	v_lshl_or_b32 v150, v153, 10, v152
	v_ashrrev_i32_e32 v151, 31, v150
	v_lshlrev_b64 v[150:151], 12, v[150:151]
	v_lshl_add_u64 v[150:151], v[4:5], 0, v[150:151]
	global_load_dwordx4 v[142:145], v[150:151], off
	global_load_dwordx4 v[146:149], v[150:151], off offset:16
	v_mad_i32_i24 v153, v153, s8, v41
	v_or_b32_e32 v150, v153, v152
	v_ashrrev_i32_e32 v151, 31, v153
	v_lshlrev_b64 v[150:151], 11, v[150:151]
	v_lshl_add_u64 v[150:151], v[2:3], 0, v[150:151]
	s_mul_i32 s98, s13, 3
	v_add_u32_e32 v165, s98, v27
	v_and_or_b32 v164, v165, s16, v23
	v_ashrrev_i32_e32 v165, 19, v165
	v_lshrrev_b32_e32 v164, 10, v164
	v_lshl_or_b32 v162, v165, 10, v164
	v_ashrrev_i32_e32 v163, 31, v162
	v_lshlrev_b64 v[162:163], 12, v[162:163]
	v_lshl_add_u64 v[162:163], v[4:5], 0, v[162:163]
	global_load_dwordx4 v[154:157], v[162:163], off
	global_load_dwordx4 v[158:161], v[162:163], off offset:16
	v_mad_i32_i24 v165, v165, s8, v41
	v_or_b32_e32 v162, v165, v164
	v_ashrrev_i32_e32 v163, 31, v165
	v_lshlrev_b64 v[162:163], 11, v[162:163]
	v_lshl_add_u64 v[162:163], v[2:3], 0, v[162:163]
	s_waitcnt vmcnt(7)
	v_cvt_pk_bf16_f32 v118, v118, v119
	v_cvt_pk_bf16_f32 v119, v120, v121
	s_waitcnt vmcnt(6)
	v_cvt_pk_bf16_f32 v120, v122, v123
	v_cvt_pk_bf16_f32 v121, v124, v125
	global_store_dwordx4 v[126:127], v[118:121], off
	s_waitcnt vmcnt(6)
	v_cvt_pk_bf16_f32 v130, v130, v131
	v_cvt_pk_bf16_f32 v131, v132, v133
	s_waitcnt vmcnt(5)
	v_cvt_pk_bf16_f32 v132, v134, v135
	v_cvt_pk_bf16_f32 v133, v136, v137
	global_store_dwordx4 v[138:139], v[130:133], off
	s_waitcnt vmcnt(5)
	v_cvt_pk_bf16_f32 v142, v142, v143
	v_cvt_pk_bf16_f32 v143, v144, v145
	s_waitcnt vmcnt(4)
	v_cvt_pk_bf16_f32 v144, v146, v147
	v_cvt_pk_bf16_f32 v145, v148, v149
	global_store_dwordx4 v[150:151], v[142:145], off
	s_waitcnt vmcnt(4)
	v_cvt_pk_bf16_f32 v154, v154, v155
	v_cvt_pk_bf16_f32 v155, v156, v157
	s_waitcnt vmcnt(3)
	v_cvt_pk_bf16_f32 v156, v158, v159
	v_cvt_pk_bf16_f32 v157, v160, v161
	global_store_dwordx4 v[162:163], v[154:157], off
	s_branch .LBB0_665
.Lxb_orig_668:
	v_and_or_b32 v7, v27, s16, v23
	v_ashrrev_i32_e32 v0, 19, v27
	v_lshrrev_b32_e32 v7, 10, v7
	v_lshl_or_b32 v42, v0, 10, v7
	v_ashrrev_i32_e32 v43, 31, v42
	v_lshlrev_b64 v[42:43], 12, v[42:43]
	v_lshl_add_u64 v[46:47], v[4:5], 0, v[42:43]
	global_load_dwordx4 v[42:45], v[46:47], off
	s_nop 0
	global_load_dwordx4 v[46:49], v[46:47], off offset:16
	v_mad_i32_i24 v0, v0, s8, v41
	v_ashrrev_i32_e32 v51, 31, v0
	v_or_b32_e32 v50, v0, v7
	v_lshlrev_b64 v[50:51], 11, v[50:51]
	s_waitcnt vmcnt(1)
	v_cvt_pk_bf16_f32 v42, v42, v43
	v_cvt_pk_bf16_f32 v43, v44, v45
	s_waitcnt vmcnt(0)
	v_cvt_pk_bf16_f32 v44, v46, v47
	v_cvt_pk_bf16_f32 v45, v48, v49
	v_lshl_add_u64 v[46:47], v[2:3], 0, v[50:51]
	global_store_dwordx4 v[46:47], v[42:45], off
	s_branch .LBB0_665

.LBB0_2207:
	s_andn2_saveexec_b64 s[6:7], s[6:7]
	s_cbranch_execz .LBB0_2204
	s_cmpk_lg_u32 s9, 0x200
	s_cbranch_scc1 .Lxb_orig_2207
	v_cmp_le_i32_e32 vcc, s9, v20
	s_cbranch_vccnz .LBB0_2204
	v_and_or_b32 v128, v27, s17, v23
	v_ashrrev_i32_e32 v129, 19, v27
	v_lshrrev_b32_e32 v128, 10, v128
	v_lshlrev_b32_e32 v126, 10, v129
	v_or3_b32 v126, v128, v126, s15
	v_ashrrev_i32_e32 v127, 31, v126
	v_lshlrev_b64 v[126:127], 12, v[126:127]
	v_lshl_add_u64 v[126:127], v[4:5], 0, v[126:127]
	global_load_dwordx4 v[118:121], v[126:127], off
	global_load_dwordx4 v[122:125], v[126:127], off offset:16
	v_mad_i32_i24 v129, v129, s8, v41
	v_or_b32_e32 v126, v129, v128
	v_ashrrev_i32_e32 v127, 31, v129
	v_lshlrev_b64 v[126:127], 11, v[126:127]
	v_lshl_add_u64 v[126:127], v[2:3], 0, v[126:127]
	s_mul_i32 s98, s13, 1
	v_add_u32_e32 v141, s98, v27
	v_and_or_b32 v140, v141, s17, v23
	v_ashrrev_i32_e32 v141, 19, v141
	v_lshrrev_b32_e32 v140, 10, v140
	v_lshlrev_b32_e32 v138, 10, v141
	v_or3_b32 v138, v140, v138, s15
	v_ashrrev_i32_e32 v139, 31, v138
	v_lshlrev_b64 v[138:139], 12, v[138:139]
	v_lshl_add_u64 v[138:139], v[4:5], 0, v[138:139]
	global_load_dwordx4 v[130:133], v[138:139], off
	global_load_dwordx4 v[134:137], v[138:139], off offset:16
	v_mad_i32_i24 v141, v141, s8, v41
	v_or_b32_e32 v138, v141, v140
	v_ashrrev_i32_e32 v139, 31, v141
	v_lshlrev_b64 v[138:139], 11, v[138:139]
	v_lshl_add_u64 v[138:139], v[2:3], 0, v[138:139]
	s_mul_i32 s98, s13, 2
	v_add_u32_e32 v153, s98, v27
	v_and_or_b32 v152, v153, s17, v23
	v_ashrrev_i32_e32 v153, 19, v153
	v_lshrrev_b32_e32 v152, 10, v152
	v_lshlrev_b32_e32 v150, 10, v153
	v_or3_b32 v150, v152, v150, s15
	v_ashrrev_i32_e32 v151, 31, v150
	v_lshlrev_b64 v[150:151], 12, v[150:151]
	v_lshl_add_u64 v[150:151], v[4:5], 0, v[150:151]
	global_load_dwordx4 v[142:145], v[150:151], off
	global_load_dwordx4 v[146:149], v[150:151], off offset:16
	v_mad_i32_i24 v153, v153, s8, v41
	v_or_b32_e32 v150, v153, v152
	v_ashrrev_i32_e32 v151, 31, v153
	v_lshlrev_b64 v[150:151], 11, v[150:151]
	v_lshl_add_u64 v[150:151], v[2:3], 0, v[150:151]
	s_mul_i32 s98, s13, 3
	v_add_u32_e32 v165, s98, v27
	v_and_or_b32 v164, v165, s17, v23
	v_ashrrev_i32_e32 v165, 19, v165
	v_lshrrev_b32_e32 v164, 10, v164
	v_lshlrev_b32_e32 v162, 10, v165
	v_or3_b32 v162, v164, v162, s15
	v_ashrrev_i32_e32 v163, 31, v162
	v_lshlrev_b64 v[162:163], 12, v[162:163]
	v_lshl_add_u64 v[162:163], v[4:5], 0, v[162:163]
	global_load_dwordx4 v[154:157], v[162:163], off
	global_load_dwordx4 v[158:161], v[162:163], off offset:16
	v_mad_i32_i24 v165, v165, s8, v41
	v_or_b32_e32 v162, v165, v164
	v_ashrrev_i32_e32 v163, 31, v165
	v_lshlrev_b64 v[162:163], 11, v[162:163]
	v_lshl_add_u64 v[162:163], v[2:3], 0, v[162:163]
	s_waitcnt vmcnt(7)
	v_cvt_pk_bf16_f32 v118, v118, v119
	v_cvt_pk_bf16_f32 v119, v120, v121
	s_waitcnt vmcnt(6)
	v_cvt_pk_bf16_f32 v120, v122, v123
	v_cvt_pk_bf16_f32 v121, v124, v125
	global_store_dwordx4 v[126:127], v[118:121], off
	s_waitcnt vmcnt(6)
	v_cvt_pk_bf16_f32 v130, v130, v131
	v_cvt_pk_bf16_f32 v131, v132, v133
	s_waitcnt vmcnt(5)
	v_cvt_pk_bf16_f32 v132, v134, v135
	v_cvt_pk_bf16_f32 v133, v136, v137
	global_store_dwordx4 v[138:139], v[130:133], off
	s_waitcnt vmcnt(5)
	v_cvt_pk_bf16_f32 v142, v142, v143
	v_cvt_pk_bf16_f32 v143, v144, v145
	s_waitcnt vmcnt(4)
	v_cvt_pk_bf16_f32 v144, v146, v147
	v_cvt_pk_bf16_f32 v145, v148, v149
	global_store_dwordx4 v[150:151], v[142:145], off
	s_waitcnt vmcnt(4)
	v_cvt_pk_bf16_f32 v154, v154, v155
	v_cvt_pk_bf16_f32 v155, v156, v157
	s_waitcnt vmcnt(3)
	v_cvt_pk_bf16_f32 v156, v158, v159
	v_cvt_pk_bf16_f32 v157, v160, v161
	global_store_dwordx4 v[162:163], v[154:157], off
	s_branch .LBB0_2204
.Lxb_orig_2207:
	v_ashrrev_i32_e32 v0, 19, v27
	v_and_or_b32 v7, v27, s17, v23
	v_lshrrev_b32_e32 v7, 10, v7
	v_lshlrev_b32_e32 v9, 10, v0
	v_or3_b32 v42, v7, v9, s15
	v_ashrrev_i32_e32 v43, 31, v42
	v_lshlrev_b64 v[42:43], 12, v[42:43]
	v_lshl_add_u64 v[50:51], v[4:5], 0, v[42:43]
	global_load_dwordx4 v[42:45], v[50:51], off
	global_load_dwordx4 v[46:49], v[50:51], off offset:16
	v_mad_i32_i24 v0, v0, s8, v41
	v_ashrrev_i32_e32 v51, 31, v0
	v_or_b32_e32 v50, v0, v7
	v_lshlrev_b64 v[50:51], 11, v[50:51]
	s_waitcnt vmcnt(1)
	v_cvt_pk_bf16_f32 v42, v42, v43
	v_cvt_pk_bf16_f32 v43, v44, v45
	s_waitcnt vmcnt(0)
	v_cvt_pk_bf16_f32 v44, v46, v47
	v_cvt_pk_bf16_f32 v45, v48, v49
	v_lshl_add_u64 v[46:47], v[2:3], 0, v[50:51]
	global_store_dwordx4 v[46:47], v[42:45], off
	s_branch .LBB0_2204
